# attention unit prologue: tiles 1 and 2 LDS-DMAs issued before the tile-0 wait (vmcnt(8) instead of vmcnt(0))
# speedup vs baseline: 1.0012x; 1.0012x over previous
; #define AT_DMA(B) do { _Pragma("unroll") for (int i_ = 0; i_ < 2; ++i_) { \
;         __builtin_amdgcn_global_load_lds((const unsigned*)kg[i_], (LAS unsigned*)(lds + (B) + dmaoff + i_ * 1024), 16, 0, 0); \
;         __builtin_amdgcn_global_load_lds((const unsigned*)vg[i_], (LAS unsigned*)(lds + (B) + AT_KBYTES + dmaoff + i_ * 1024), 16, 0, 0); } } while (0)
; #define AT_ADV() do { kg[0] += 64 * 1024; kg[1] += 64 * 1024; vg[0] += 64; vg[1] += 64; } while (0)
; __device__ __forceinline__ void attn_unit(unsigned char* ws, const float* sub_g, LAS unsigned char* lds, int h, int qb, float negM, float lam) {
;     ...
;     const int qrow0 = qb * 128 + 32 * wq;
;     const bf16_t* Qp = (const bf16_t*)(ws + WS_Q); const bf16_t* Kp = (const bf16_t*)(ws + WS_K); const bf16_t* VTp = (const bf16_t*)(ws + WS_VT);
;     bf16x8 qf[4];
;     {
;         const bf16_t* qp = Qp + (size_t)(qrow0 + r32) * 1024 + (h * 2 + map) * 64 + 8 * hi;
; #pragma unroll
;         for (int d0 = 0; d0 < 4; ++d0) qf[d0] = *(const bf16x8*)(qp + 16 * d0);
;     }
;     const bf16_t* kg[2]; const bf16_t* vg[2];
; #pragma unroll
;     for (int i = 0; i < 2; ++i) {
;         const int g = 2 * wid + i;
;         const int kr = 4 * g + (lane >> 4), kc = (lane & 15) ^ (kr & 15);
;         kg[i] = Kp + (size_t)kr * 1024 + h * 128 + kc * 8;
;         const int vr = 8 * g + (lane >> 3), vc = (lane & 7) ^ ((vr >> 1) & 7);
;         vg[i] = VTp + (size_t)(h * 128 + vr) * NTOK + vc * 8;
;     }
;     const unsigned dmaoff = (unsigned)wid * 2048u;
;     ...
;     int kad[4], vad[4];
; #pragma unroll
;     for (int d0 = 0; d0 < 4; ++d0) kad[d0] = r32 * 256 + (((map * 8 + 2 * d0 + hi) ^ (r32 & 15)) << 4);
; #pragma unroll
;     for (int j = 0; j < 4; ++j) vad[j] = AT_KBYTES + r32 * 128 + (((2 * j + hi) ^ ((r32 >> 1) & 7)) << 4);
;     ...
;     f32x16 o[4];
; #pragma unroll
;     for (int b = 0; b < 4; ++b)
; #pragma unroll
;         for (int r = 0; r < 16; ++r) o[b][r] = 0.f;
;     f32x16 negm;
; #pragma unroll
;     for (int r = 0; r < 16; ++r) negm[r] = negM;
;     float l0 = 0.f, l1 = 0.f;
;     AT_DMA(0); AT_ADV();
;     asm volatile("s_waitcnt vmcnt(0)" ::: "memory");
;     __builtin_amdgcn_s_barrier();
;     AT_DMA(AT_BUF); AT_ADV();
.LBB0_830:
	v_readfirstlane_b32 s25, v220
	s_bfe_u32 s29, s25, 0x20006
	s_lshl_b32 s8, s20, 4
	s_and_b32 s8, s8, 0xffffff80
	s_lshl_b32 s21, s29, 5
	s_or_b32 s21, s21, s8
	s_lshr_b32 s28, s25, 8
	v_or_b32_e32 v16, s21, v153
	s_lshl_b32 s8, s20, 7
	v_ashrrev_i32_e32 v17, 31, v16
	s_and_b32 s24, s8, 0x380
	s_lshl_b32 s8, s28, 6
	v_lshlrev_b64 v[16:17], 11, v[16:17]
	s_add_i32 s8, s8, s24
	v_lshl_add_u64 v[16:17], s[4:5], 0, v[16:17]
	s_lshl_b32 s8, s8, 1
	v_lshl_add_u64 v[16:17], v[16:17], 0, s[8:9]
	v_lshlrev_b32_e32 v130, 4, v150
	s_mov_b64 s[34:35], 0x8000
	v_lshl_add_u64 v[16:17], v[16:17], 0, v[130:131]
	v_lshl_add_u64 v[18:19], v[16:17], 0, s[34:35]
	global_load_dwordx4 v[112:115], v[16:17], off
	global_load_dwordx4 v[116:119], v[16:17], off offset:64
	global_load_dwordx4 v[120:123], v[18:19], off
	global_load_dwordx4 v[124:127], v[18:19], off offset:64
	s_lshr_b32 s33, s25, 6
	s_lshr_b32 s8, s25, 5
	s_lshl_b32 s30, s24, 1
	s_add_u32 s30, s3, s30
	s_addc_u32 s31, s18, 0
	s_lshl_b32 s34, s33, 3
	s_bfe_u32 s98, s25, 0x10007
	s_lshl_b32 s98, s98, 3
	s_or_b32 s99, s98, 4
	v_or_b32_e32 v130, s34, v150
	v_bitop3_b32 v18, s98, v220, v150 bitop3:0x36
	v_lshlrev_b64 v[16:17], 11, v[130:131]
	v_lshlrev_b32_e32 v18, 4, v18
	v_lshl_add_u64 v[16:17], s[30:31], 0, v[16:17]
	v_and_b32_e32 v130, 0xf0, v18
	v_lshl_add_u64 v[56:57], v[16:17], 0, v[130:131]
	v_lshl_or_b32 v16, s33, 4, v151
	v_lshrrev_b32_e32 v17, 1, v151
	v_xor_b32_e32 v20, v17, v220
	v_add_u32_e32 v18, s24, v16
	v_mov_b64_e32 v[16:17], s[6:7]
	v_mad_u64_u32 v[18:19], s[34:35], v18, s19, v[16:17]
	v_lshlrev_b32_e32 v20, 4, v20
	s_or_b32 s8, s8, 1
	v_and_b32_e32 v130, 0x70, v20
	s_lshl_b32 s34, s8, 2
	v_lshl_add_u64 v[58:59], v[18:19], 0, v[130:131]
	v_or_b32_e32 v130, s34, v150
	v_bitop3_b32 v20, s99, v220, v150 bitop3:0x36
	v_lshlrev_b64 v[18:19], 11, v[130:131]
	v_lshlrev_b32_e32 v20, 4, v20
	v_lshl_add_u64 v[18:19], s[30:31], 0, v[18:19]
	v_and_b32_e32 v130, 0xf0, v20
	v_lshl_add_u64 v[60:61], v[18:19], 0, v[130:131]
	v_lshl_or_b32 v18, s8, 3, v151
	v_lshrrev_b32_e32 v19, 1, v18
	v_add_u32_e32 v18, s24, v18
	s_lshl_b32 s8, s33, 11
	v_mad_u64_u32 v[16:17], s[30:31], v18, s19, v[16:17]
	s_add_i32 s8, s8, 0
	v_xor_b32_e32 v19, v19, v220
	s_add_i32 s31, s8, 0x4000
	s_mov_b32 m0, s8
	v_lshlrev_b32_e32 v18, 4, v19
	global_load_lds_dwordx4 v[56:57], off
	s_mov_b32 m0, s31
	v_and_b32_e32 v130, 0x70, v18
	global_load_lds_dwordx4 v[58:59], off
	s_add_i32 m0, s8, 0x400
	v_lshl_add_u64 v[62:63], v[16:17], 0, v[130:131]
	global_load_lds_dwordx4 v[60:61], off
	s_add_i32 m0, s8, 0x4400
	v_lshl_add_u64 v[16:17], v[56:57], 0, s[10:11]
	global_load_lds_dwordx4 v[62:63], off
	s_add_i32 m0, s8, 0x8000
	s_add_i32 s31, s8, 0xc000
	v_lshl_add_u64 v[20:21], v[58:59], 0, s[12:13]
	global_load_lds_dwordx4 v[16:17], off
	s_mov_b32 m0, s31
	v_lshl_add_u64 v[18:19], v[60:61], 0, s[10:11]
	global_load_lds_dwordx4 v[20:21], off
	s_add_i32 m0, s8, 0x8400
	v_lshl_add_u64 v[22:23], v[62:63], 0, s[12:13]
	global_load_lds_dwordx4 v[18:19], off
	s_add_i32 m0, s8, 0xc400
	s_lshl_b32 s30, s28, 3
	global_load_lds_dwordx4 v[22:23], off
	v_lshl_add_u64 v[140:141], v[56:57], 0, s[14:15]
	v_lshl_add_u64 v[142:143], v[60:61], 0, s[14:15]
	v_lshl_add_u64 v[144:145], v[58:59], 0, s[16:17]
	v_lshl_add_u64 v[146:147], v[62:63], 0, s[16:17]
	s_add_i32 m0, s8, 0x10000
	s_nop 0
	global_load_lds_dwordx4 v[140:141], off
	s_add_i32 m0, s8, 0x14000
	s_nop 0
	global_load_lds_dwordx4 v[144:145], off
	s_add_i32 m0, s8, 0x10400
	s_nop 0
	global_load_lds_dwordx4 v[142:143], off
	s_add_i32 m0, s8, 0x14400
	s_nop 0
	global_load_lds_dwordx4 v[146:147], off
	s_waitcnt vmcnt(8)
	s_barrier
; #define AT_DMA(B) do { _Pragma("unroll") for (int i_ = 0; i_ < 2; ++i_) { \
;         __builtin_amdgcn_global_load_lds((const unsigned*)kg[i_], (LAS unsigned*)(lds + (B) + dmaoff + i_ * 1024), 16, 0, 0); \
;         __builtin_amdgcn_global_load_lds((const unsigned*)vg[i_], (LAS unsigned*)(lds + (B) + AT_KBYTES + dmaoff + i_ * 1024), 16, 0, 0); } } while (0)
; #define AT_ADV() do { kg[0] += 64 * 1024; kg[1] += 64 * 1024; vg[0] += 64; vg[1] += 64; } while (0)
; __device__ __forceinline__ void attn_unit(unsigned char* ws, const float* sub_g, LAS unsigned char* lds, int h, int qb, float negM, float lam) {
;     ...
;     AT_DMA(AT_BUF); AT_ADV();
;     f32x16 pa, pb;
;     {
;         f32x16 s0 = negm, s1 = negm;
; #pragma unroll
;         for (int d0 = 0; d0 < 4; ++d0) { s0 = __builtin_amdgcn_mfma_f32_32x32x16_bf16(KFR(0, d0, 0), qf[d0], s0, 0, 0, 0); s1 = __builtin_amdgcn_mfma_f32_32x32x16_bf16(KFR(0, d0, 1), qf[d0], s1, 0, 0, 0); }
; #pragma unroll
;         for (int r = 0; r < 16; ++r) { pa[r] = __builtin_amdgcn_exp2f(s0[r]); pb[r] = __builtin_amdgcn_exp2f(s1[r]); }
;     }
;     asm volatile("s_waitcnt vmcnt(0) lgkmcnt(0)" ::: "memory");
;     __builtin_amdgcn_s_barrier();
;     int bV = 0, bK = AT_BUF, bW = 2 * AT_BUF;
	v_lshl_add_u64 v[140:141], v[140:141], 0, s[10:11]
	v_lshl_add_u64 v[142:143], v[142:143], 0, s[10:11]
	v_lshl_add_u64 v[144:145], v[144:145], 0, s[12:13]
	v_lshl_add_u64 v[146:147], v[146:147], 0, s[12:13]
	s_mov_b32 s98, s3
	s_mov_b32 s99, s18
	s_mov_b64 s[100:101], s[6:7]
	v_subrev_u32_e32 v140, s3, v140
	v_subrev_u32_e32 v142, s3, v142
	v_subrev_u32_e32 v144, s6, v144
	v_subrev_u32_e32 v146, s6, v146
	s_mov_b32 s33, 1
	v_bitop3_b32 v24, s30, v153, v150 bitop3:0x36
	v_lshlrev_b32_e32 v25, 8, v153
	v_and_b32_e32 v26, 0x700, v25
	v_and_b32_e32 v25, 0x800, v25
	v_lshl_or_b32 v26, v25, 1, v26
	v_lshl_add_u32 v198, v24, 4, v26
	v_xor_b32_e32 v200, 64, v198
	v_lshrrev_b32_e32 v24, 1, v153
	v_xor_b32_e32 v24, v24, v150
	v_lshlrev_b32_e32 v25, 7, v153
	v_lshl_add_u32 v201, v24, 4, v25
	v_xor_b32_e32 v202, 64, v201
	v_add_u32_e32 v247, 0x10000, v198
	v_add_u32_e32 v248, 0x10000, v200
	v_add_u32_e32 v249, 0x10000, v201
	v_add_u32_e32 v250, 0x10000, v202
	ds_read_b128 v[16:19], v198
	ds_read_b128 v[20:23], v200
	ds_read_b128 v[24:27], v198 offset:2048
	ds_read_b128 v[28:31], v200 offset:2048
	ds_read_b128 v[32:35], v198 offset:8192
	ds_read_b128 v[36:39], v200 offset:8192
	ds_read_b128 v[40:43], v198 offset:10240
	ds_read_b128 v[44:47], v200 offset:10240
	s_waitcnt lgkmcnt(7)
	v_mfma_f32_16x16x32_bf16 v[80:83], v[16:19], v[112:115], v[0:3]
	v_mfma_f32_16x16x32_bf16 v[84:87], v[16:19], v[120:123], v[0:3]
	s_waitcnt lgkmcnt(6)
	v_mfma_f32_16x16x32_bf16 v[80:83], v[20:23], v[116:119], v[80:83]
	v_mfma_f32_16x16x32_bf16 v[84:87], v[20:23], v[124:127], v[84:87]
	s_waitcnt lgkmcnt(5)
	v_mfma_f32_16x16x32_bf16 v[88:91], v[24:27], v[112:115], v[0:3]
	v_mfma_f32_16x16x32_bf16 v[92:95], v[24:27], v[120:123], v[0:3]
	s_waitcnt lgkmcnt(4)
	v_mfma_f32_16x16x32_bf16 v[88:91], v[28:31], v[116:119], v[88:91]
	v_mfma_f32_16x16x32_bf16 v[92:95], v[28:31], v[124:127], v[92:95]
	s_waitcnt lgkmcnt(3)
	v_mfma_f32_16x16x32_bf16 v[96:99], v[32:35], v[112:115], v[0:3]
	v_mfma_f32_16x16x32_bf16 v[100:103], v[32:35], v[120:123], v[0:3]
	s_waitcnt lgkmcnt(2)
	v_mfma_f32_16x16x32_bf16 v[96:99], v[36:39], v[116:119], v[96:99]
	v_mfma_f32_16x16x32_bf16 v[100:103], v[36:39], v[124:127], v[100:103]
	s_waitcnt lgkmcnt(1)
	v_mfma_f32_16x16x32_bf16 v[104:107], v[40:43], v[112:115], v[0:3]
	v_mfma_f32_16x16x32_bf16 v[108:111], v[40:43], v[120:123], v[0:3]
	s_waitcnt lgkmcnt(0)
	v_mfma_f32_16x16x32_bf16 v[104:107], v[44:47], v[116:119], v[104:107]
	v_mfma_f32_16x16x32_bf16 v[108:111], v[44:47], v[124:127], v[108:111]
	s_nop 7
	s_nop 1
	v_exp_f32_e32 v183, v80
	v_exp_f32_e32 v184, v81
	v_exp_f32_e32 v185, v82
	v_exp_f32_e32 v186, v83
	v_exp_f32_e32 v187, v84
	v_exp_f32_e32 v188, v85
	v_exp_f32_e32 v189, v86
	v_exp_f32_e32 v190, v87
	v_exp_f32_e32 v191, v88
	v_exp_f32_e32 v192, v89
	v_exp_f32_e32 v193, v90
	v_exp_f32_e32 v194, v91
	v_exp_f32_e32 v195, v92
	v_exp_f32_e32 v196, v93
	v_exp_f32_e32 v197, v94
	v_exp_f32_e32 v199, v95
	v_exp_f32_e32 v203, v96
	v_exp_f32_e32 v204, v97
	v_exp_f32_e32 v205, v98
	v_exp_f32_e32 v206, v99
	v_exp_f32_e32 v207, v100
	v_exp_f32_e32 v208, v101
	v_exp_f32_e32 v209, v102
	v_exp_f32_e32 v210, v103
	v_exp_f32_e32 v211, v104
	v_exp_f32_e32 v213, v105
	v_exp_f32_e32 v214, v106
	v_exp_f32_e32 v215, v107
	v_exp_f32_e32 v216, v108
	v_exp_f32_e32 v217, v109
	v_exp_f32_e32 v218, v110
	v_exp_f32_e32 v219, v111
	v_mov_b32_e32 v16, 0
	v_mov_b32_e32 v17, 0
	v_mov_b32_e32 v18, 0
	v_mov_b32_e32 v19, 0
	v_mov_b32_e32 v20, 0
	v_mov_b32_e32 v21, 0
	v_mov_b32_e32 v22, 0
	v_mov_b32_e32 v23, 0
	v_mov_b32_e32 v24, 0
	v_mov_b32_e32 v25, 0
	v_mov_b32_e32 v26, 0
	v_mov_b32_e32 v27, 0
	v_mov_b32_e32 v28, 0
	v_mov_b32_e32 v29, 0
	v_mov_b32_e32 v30, 0
	v_mov_b32_e32 v31, 0
	v_mov_b32_e32 v32, 0
	v_mov_b32_e32 v33, 0
	v_mov_b32_e32 v34, 0
	v_mov_b32_e32 v35, 0
	v_mov_b32_e32 v36, 0
	v_mov_b32_e32 v37, 0
	v_mov_b32_e32 v38, 0
	v_mov_b32_e32 v39, 0
	v_mov_b32_e32 v40, 0
	v_mov_b32_e32 v41, 0
	v_mov_b32_e32 v42, 0
	v_mov_b32_e32 v43, 0
	v_mov_b32_e32 v44, 0
	v_mov_b32_e32 v45, 0
	v_mov_b32_e32 v46, 0
	v_mov_b32_e32 v47, 0
	v_mov_b32_e32 v48, 0
	v_mov_b32_e32 v49, 0
	v_mov_b32_e32 v50, 0
	v_mov_b32_e32 v51, 0
	v_mov_b32_e32 v52, 0
	v_mov_b32_e32 v53, 0
	v_mov_b32_e32 v54, 0
	v_mov_b32_e32 v55, 0
	v_mov_b32_e32 v56, 0
	v_mov_b32_e32 v57, 0
	v_mov_b32_e32 v58, 0
	v_mov_b32_e32 v59, 0
	v_mov_b32_e32 v60, 0
	v_mov_b32_e32 v61, 0
	v_mov_b32_e32 v62, 0
	v_mov_b32_e32 v63, 0
	v_mov_b32_e32 v64, 0
	v_mov_b32_e32 v65, 0
	v_mov_b32_e32 v66, 0
	v_mov_b32_e32 v67, 0
	v_mov_b32_e32 v68, 0
	v_mov_b32_e32 v69, 0
	v_mov_b32_e32 v70, 0
	v_mov_b32_e32 v71, 0
	v_mov_b32_e32 v72, 0
	v_mov_b32_e32 v73, 0
	v_mov_b32_e32 v74, 0
	v_mov_b32_e32 v75, 0
	v_mov_b32_e32 v76, 0
	v_mov_b32_e32 v77, 0
	v_mov_b32_e32 v78, 0
	v_mov_b32_e32 v79, 0
	v_mov_b32_e32 v222, 0
	v_mov_b32_e32 v223, 0
	s_waitcnt vmcnt(4)
	s_barrier
	ds_read_b128 v[4:7], v198 offset:32768
	ds_read_b128 v[8:11], v200 offset:32768
	ds_read_b128 v[12:15], v198 offset:34816
	s_branch .Lattn_c1
